# plus: hg3 epilogue gain loads hoisted, P0 norm loop rewritten (scalar index math, all loads up front)
# speedup vs baseline: 1.0723x; 1.0104x over previous
; #define OPQ int tid = tid0; asm volatile("" : "+v"(tid));
; DEV void norm_item(const Params& p, int l, int g, int item, int tid) {
;   const int wid = tid >> 6, lane = tid & 63;
;   const int r = item * 8 + wid;
;   const int bl = r / NTOK, j = r % NTOK, b = g * G + bl;
;   const float* src;
;   int mrow;
;   if (j < NCTX) {
;     src = (l == 0 ? p.ctx : p.hctx) + ((long)b * NCTX + j) * D;
;     mrow = 32;
;   } else {
;     src = (l == 0 ? p.x : p.out) + ((long)b * SEQ + (j - NCTX)) * D;
;     mrow = b;
;   }
;   const float* md = p.mod + ((long)l * 33 + mrow) * 3072;
;   const float* ng = p.norm_g + l * D;
;   float4 v[4];
;   float ss = 0.f;
; #pragma unroll
;   for (int i = 0; i < 4; ++i) {
;     v[i] = *(const float4*)(src + i * 256 + lane * 4);
;     ss += v[i].x * v[i].x + v[i].y * v[i].y + v[i].z * v[i].z + v[i].w * v[i].w;
;   }
;   ss = wsum(ss, lane);
;   const float rstd = rsqrtf(ss * (1.f / D) + 1e-6f);
; #pragma unroll
;   for (int i = 0; i < 4; ++i) {
;     int col = i * 256 + lane * 4;
;     float4 gg = *(const float4*)(ng + col);
;     float4 sh = *(const float4*)(md + col);
;     float4 sc = *(const float4*)(md + 1024 + col);
;     uint2 o;
;     o.x = pack2(v[i].x * rstd * gg.x * (1.f + sc.x) + sh.x, v[i].y * rstd * gg.y * (1.f + sc.y) + sh.y);
;     o.y = pack2(v[i].z * rstd * gg.z * (1.f + sc.z) + sh.z, v[i].w * rstd * gg.w * (1.f + sc.w) + sh.w);
;     *(uint2*)(p.u + (long)r * D + col) = o;
;   }
; __global__ void __launch_bounds__(512) mega(Params p, int coop) {
;     ...
;         for (int it = bid; it < TG / 8; it += nb) { OPQ norm_item(p, l, g, it, tid); }
.LBB0_104:
	s_cmp_eq_u32 s14, 0
	s_cselect_b64 s[6:7], -1, 0
	v_writelane_b32 v255, s6, 38
	s_lshl_b32 s24, s14, 10
	s_nop 0
	v_writelane_b32 v255, s7, 39
	v_readlane_b32 s6, v253, 23
	v_readlane_b32 s7, v253, 24
	s_andn2_b64 vcc, exec, s[6:7]
	s_cbranch_vccnz .LBB0_111
	v_readlane_b32 s6, v255, 38
	v_readlane_b32 s7, v255, 39
	s_and_b64 s[6:7], s[6:7], exec
	s_cselect_b32 s6, 0, 0x98
	s_cselect_b32 s8, 16, 0xe0
	s_lshl_b64 s[12:13], s[24:25], 2
	v_readlane_b32 s16, v255, 15
	v_readlane_b32 s17, v255, 16
	s_add_u32 s16, s16, s12
	s_mov_b32 s7, s25
	s_mov_b32 s9, s25
	s_mul_i32 s10, s14, 33
	s_mov_b32 s11, s25
	s_addc_u32 s17, s17, s13
	v_readlane_b32 s15, v254, 36
	s_mov_b32 s18, s75
	v_readlane_b32 s12, v253, 0
	v_readlane_b32 s13, v253, 1
	v_lshrrev_b32_e32 v0, 6, v197
	s_load_dwordx2 s[56:57], s[12:13], s6
	s_load_dwordx2 s[58:59], s[12:13], s8
	v_and_b32_e32 v1, 63, v197
	v_readfirstlane_b32 s60, v0
	v_lshlrev_b32_e32 v156, 4, v1
	v_lshlrev_b32_e32 v50, 3, v1
	v_lshlrev_b32_e32 v51, 2, v197
	v_xor_b32_e32 v64, 0x80, v51
	v_and_b32_e32 v64, 0xfc, v64
	v_xor_b32_e32 v65, 0x40, v51
	v_and_b32_e32 v65, 0xfc, v65
	v_xor_b32_e32 v66, 0x20, v51
	v_and_b32_e32 v66, 0xfc, v66
	v_xor_b32_e32 v67, 0x10, v51
	v_and_b32_e32 v67, 0xfc, v67
	v_xor_b32_e32 v68, 0x8, v51
	v_and_b32_e32 v68, 0xfc, v68
	v_xor_b32_e32 v69, 0x4, v51
	v_and_b32_e32 v69, 0xfc, v69
	s_waitcnt lgkmcnt(0)
; DEV void norm_item(const Params& p, int l, int g, int item, int tid) {
;   const int wid = tid >> 6, lane = tid & 63;
;   const int r = item * 8 + wid;
;   const int bl = r / NTOK, j = r % NTOK, b = g * G + bl;
;   const float* src;
;   int mrow;
;   if (j < NCTX) {
;     src = (l == 0 ? p.ctx : p.hctx) + ((long)b * NCTX + j) * D;
;     mrow = 32;
;   } else {
;     src = (l == 0 ? p.x : p.out) + ((long)b * SEQ + (j - NCTX)) * D;
;     mrow = b;
;   }
;   const float* md = p.mod + ((long)l * 33 + mrow) * 3072;
;   const float* ng = p.norm_g + l * D;
;   float4 v[4];
;   float ss = 0.f;
; #pragma unroll
;   for (int i = 0; i < 4; ++i) {
;     v[i] = *(const float4*)(src + i * 256 + lane * 4);
;     ss += v[i].x * v[i].x + v[i].y * v[i].y + v[i].z * v[i].z + v[i].w * v[i].w;
;   }
;   ss = wsum(ss, lane);
;   const float rstd = rsqrtf(ss * (1.f / D) + 1e-6f);
; #pragma unroll
;   for (int i = 0; i < 4; ++i) {
;     int col = i * 256 + lane * 4;
;     float4 gg = *(const float4*)(ng + col);
;     float4 sh = *(const float4*)(md + col);
;     float4 sc = *(const float4*)(md + 1024 + col);
;     uint2 o;
;     o.x = pack2(v[i].x * rstd * gg.x * (1.f + sc.x) + sh.x, v[i].y * rstd * gg.y * (1.f + sc.y) + sh.y);
;     o.y = pack2(v[i].z * rstd * gg.z * (1.f + sc.z) + sh.z, v[i].w * rstd * gg.w * (1.f + sc.w) + sh.w);
;     *(uint2*)(p.u + (long)r * D + col) = o;
;   }
.Lp0_loop:
	s_add_i32 s19, s15, s60
	s_mul_hi_u32 s32, s19, 0x38e38e39
	s_lshr_b32 s32, s32, 9
	s_mul_i32 s11, s32, 0x900
	s_sub_i32 s61, s19, s11
	s_lshl_b32 s12, s19, 11
	s_add_u32 s12, s86, s12
	s_addc_u32 s13, s87, 0
	v_readlane_b32 s19, v255, 29
	s_nop 0
	s_add_i32 s32, s32, s19
	s_add_i32 s19, s61, 0xffffff00
	s_cmp_lt_u32 s61, 0x100
	s_cselect_b32 s62, s58, s56
	s_cselect_b32 s63, s59, s57
	s_cselect_b32 s11, 20, 23
	s_cselect_b32 s79, 32, s32
	s_cselect_b32 s19, s61, s19
	s_lshl_b32 s32, s32, s11
	s_lshl_b32 s19, s19, 12
	s_add_u32 s32, s32, s19
	s_add_u32 s62, s62, s32
	s_addc_u32 s63, s63, 0
	s_add_i32 s79, s79, s10
	s_mul_i32 s79, s79, 0x3000
	v_readlane_b32 s19, v253, 21
	v_readlane_b32 s32, v253, 22
	s_nop 0
	s_add_u32 s6, s19, s79
	s_addc_u32 s7, s32, 0
	s_add_u32 s8, s6, 0x1000
	s_addc_u32 s9, s7, 0
	global_load_dwordx4 v[4:7], v156, s[62:63]
	global_load_dwordx4 v[8:11], v156, s[62:63] offset:1024
	global_load_dwordx4 v[12:15], v156, s[62:63] offset:2048
	global_load_dwordx4 v[16:19], v156, s[62:63] offset:3072
	global_load_dwordx4 v[20:23], v156, s[8:9]
	global_load_dwordx4 v[24:27], v156, s[16:17]
	global_load_dwordx4 v[28:31], v156, s[6:7]
	global_load_dwordx4 v[96:99], v156, s[16:17] offset:1024
	global_load_dwordx4 v[108:111], v156, s[8:9] offset:1024
	global_load_dwordx4 v[120:123], v156, s[6:7] offset:1024
	global_load_dwordx4 v[100:103], v156, s[16:17] offset:2048
	global_load_dwordx4 v[112:115], v156, s[8:9] offset:2048
	global_load_dwordx4 v[124:127], v156, s[6:7] offset:2048
	global_load_dwordx4 v[104:107], v156, s[16:17] offset:3072
	global_load_dwordx4 v[116:119], v156, s[8:9] offset:3072
	global_load_dwordx4 v[128:131], v156, s[6:7] offset:3072
	s_mov_b32 s11, 0x800000
	s_waitcnt vmcnt(12)
	v_mov_b32_e32 v40, v5
	v_mov_b32_e32 v41, v9
	v_mov_b32_e32 v38, v4
	v_mov_b32_e32 v39, v8
	v_mov_b32_e32 v48, v13
	v_mov_b32_e32 v49, v17
	v_pk_mul_f32 v[40:41], v[40:41], v[40:41]
	v_mov_b32_e32 v2, v6
	v_mov_b32_e32 v3, v10
	v_mov_b32_e32 v46, v12
	v_mov_b32_e32 v47, v16
	v_pk_mul_f32 v[48:49], v[48:49], v[48:49]
	v_pk_fma_f32 v[38:39], v[38:39], v[38:39], v[40:41]
	v_mov_b32_e32 v36, v7
	v_mov_b32_e32 v37, v11
	v_mov_b32_e32 v42, v14
	v_mov_b32_e32 v43, v18
	v_pk_fma_f32 v[40:41], v[46:47], v[46:47], v[48:49]
	v_pk_fma_f32 v[2:3], v[2:3], v[2:3], v[38:39]
	v_mov_b32_e32 v44, v15
	v_mov_b32_e32 v45, v19
	v_pk_fma_f32 v[38:39], v[42:43], v[42:43], v[40:41]
	v_pk_fma_f32 v[2:3], v[36:37], v[36:37], v[2:3]
	v_pk_fma_f32 v[36:37], v[44:45], v[44:45], v[38:39]
	v_add_f32_e32 v2, v2, v3
	v_add_f32_e32 v2, v2, v36
	v_add_f32_e32 v2, v2, v37
	ds_bpermute_b32 v1, v64, v2
	s_waitcnt lgkmcnt(0)
	v_add_f32_e32 v1, v2, v1
	ds_bpermute_b32 v2, v65, v1
	s_waitcnt lgkmcnt(0)
	v_add_f32_e32 v1, v1, v2
	ds_bpermute_b32 v2, v66, v1
	s_waitcnt lgkmcnt(0)
	v_add_f32_e32 v2, v1, v2
	ds_bpermute_b32 v3, v67, v2
	s_waitcnt lgkmcnt(0)
	v_add_f32_e32 v2, v2, v3
	ds_bpermute_b32 v36, v68, v2
	s_waitcnt lgkmcnt(0)
	v_add_f32_e32 v40, v2, v36
	ds_bpermute_b32 v41, v69, v40
	s_waitcnt vmcnt(11)
	v_pk_add_f32 v[2:3], v[22:23], 1.0 op_sel_hi:[1,0]
	s_waitcnt lgkmcnt(0)
	v_add_f32_e32 v0, v40, v41
	v_fmamk_f32 v0, v0, 0x3a800000, v196
	v_mul_f32_e32 v1, 0x4b800000, v0
	v_cmp_gt_f32_e32 vcc, s11, v0
	s_nop 1
	v_cndmask_b32_e32 v0, v0, v1, vcc
	v_rsq_f32_e32 v40, v0
	v_pk_add_f32 v[0:1], v[20:21], 1.0 op_sel_hi:[1,0]
	v_mul_f32_e32 v20, 0x45800000, v40
	v_cndmask_b32_e32 v40, v40, v20, vcc
	v_pk_mul_f32 v[4:5], v[4:5], v[40:41] op_sel_hi:[1,0]
	v_pk_mul_f32 v[6:7], v[6:7], v[40:41] op_sel_hi:[1,0]
	s_waitcnt vmcnt(10)
	v_pk_mul_f32 v[4:5], v[24:25], v[4:5]
	v_pk_mul_f32 v[6:7], v[26:27], v[6:7]
	s_waitcnt vmcnt(9)
	v_pk_fma_f32 v[0:1], v[0:1], v[4:5], v[28:29]
	v_pk_fma_f32 v[2:3], v[2:3], v[6:7], v[30:31]
	v_cvt_pk_bf16_f32 v0, v0, v1
	v_cvt_pk_bf16_f32 v1, v2, v3
	global_store_dwordx2 v50, v[0:1], s[12:13]
	v_pk_mul_f32 v[8:9], v[8:9], v[40:41] op_sel_hi:[1,0]
	v_pk_mul_f32 v[10:11], v[10:11], v[40:41] op_sel_hi:[1,0]
	s_waitcnt vmcnt(9)
	v_pk_mul_f32 v[0:1], v[8:9], v[96:97]
	v_pk_mul_f32 v[2:3], v[10:11], v[98:99]
	s_waitcnt vmcnt(8)
	v_pk_add_f32 v[20:21], v[108:109], 1.0 op_sel_hi:[1,0]
	v_pk_add_f32 v[22:23], v[110:111], 1.0 op_sel_hi:[1,0]
	s_waitcnt vmcnt(7)
	v_pk_fma_f32 v[0:1], v[0:1], v[20:21], v[120:121]
	v_pk_fma_f32 v[2:3], v[2:3], v[22:23], v[122:123]
	v_cvt_pk_bf16_f32 v0, v0, v1
	v_cvt_pk_bf16_f32 v1, v2, v3
	global_store_dwordx2 v50, v[0:1], s[12:13] offset:512
	v_pk_mul_f32 v[12:13], v[12:13], v[40:41] op_sel_hi:[1,0]
	v_pk_mul_f32 v[14:15], v[14:15], v[40:41] op_sel_hi:[1,0]
	s_waitcnt vmcnt(7)
	v_pk_mul_f32 v[0:1], v[12:13], v[100:101]
	v_pk_mul_f32 v[2:3], v[14:15], v[102:103]
	s_waitcnt vmcnt(6)
	v_pk_add_f32 v[20:21], v[112:113], 1.0 op_sel_hi:[1,0]
	v_pk_add_f32 v[22:23], v[114:115], 1.0 op_sel_hi:[1,0]
	s_waitcnt vmcnt(5)
	v_pk_fma_f32 v[0:1], v[0:1], v[20:21], v[124:125]
	v_pk_fma_f32 v[2:3], v[2:3], v[22:23], v[126:127]
	v_cvt_pk_bf16_f32 v0, v0, v1
	v_cvt_pk_bf16_f32 v1, v2, v3
	global_store_dwordx2 v50, v[0:1], s[12:13] offset:1024
	v_pk_mul_f32 v[16:17], v[16:17], v[40:41] op_sel_hi:[1,0]
	v_pk_mul_f32 v[18:19], v[18:19], v[40:41] op_sel_hi:[1,0]
	s_waitcnt vmcnt(5)
	v_pk_mul_f32 v[0:1], v[16:17], v[104:105]
	v_pk_mul_f32 v[2:3], v[18:19], v[106:107]
	s_waitcnt vmcnt(4)
	v_pk_add_f32 v[20:21], v[116:117], 1.0 op_sel_hi:[1,0]
	v_pk_add_f32 v[22:23], v[118:119], 1.0 op_sel_hi:[1,0]
	s_waitcnt vmcnt(3)
	v_pk_fma_f32 v[0:1], v[0:1], v[20:21], v[128:129]
	v_pk_fma_f32 v[2:3], v[2:3], v[22:23], v[130:131]
	v_cvt_pk_bf16_f32 v0, v0, v1
	v_cvt_pk_bf16_f32 v1, v2, v3
	global_store_dwordx2 v50, v[0:1], s[12:13] offset:1536
	v_readlane_b32 s19, v253, 2
	v_readlane_b32 s32, v255, 27
	s_nop 0
	s_add_i32 s18, s18, s19
	s_add_i32 s15, s15, s32
	s_cmpk_gt_i32 s18, 0x8ff
	s_cbranch_scc0 .Lp0_loop

; DEV float bf2f(u16 h) { return __uint_as_float(((unsigned)h) << 16); }
; DEV float flog(float x) { return __builtin_amdgcn_logf(x) * 0.6931471805599453f; }
; DEV void hg_prep(int dir, int qu, int lane, char* smem, const u16 (&kr)[16], float (&g)[16], float (&kk)[16]) {
; #pragma unroll
;   for (int i = 0; i < 16; ++i) {
;     kk[i] = bf2f(kr[i]);
;     g[i] = fmaxf(flog(1.f - kk[i]), -20.f);
;   }
;   float total;
;   if (dir == 0) {
; #pragma unroll
;     for (int i = 1; i < 16; ++i) g[i] += g[i - 1];
;     total = g[15];
;   } else {
; #pragma unroll
;     for (int i = 14; i >= 0; --i) g[i] += g[i + 1];
;     total = g[0];
;   }
;   ((float*)(smem + H_TOT))[(dir * 4 + qu) * 64 + lane] = total;
.LBB0_1056:
	s_or_b64 exec, exec, s[12:13]
	v_lshlrev_b32_e32 v158, 16, v19
	v_sub_f32_e32 v0, 1.0, v158
	v_lshlrev_b32_e32 v155, 16, v16
	v_log_f32_e32 v0, v0
	v_sub_f32_e32 v1, 1.0, v155
	v_log_f32_e32 v1, v1
	v_lshlrev_b32_e32 v154, 16, v18
	v_mul_f32_e32 v0, 0x3f317218, v0
	v_max_f32_e32 v16, 0xc1a00000, v0
	v_mul_f32_e32 v0, 0x3f317218, v1
	v_sub_f32_e32 v1, 1.0, v154
	v_lshlrev_b32_e32 v153, 16, v17
	v_log_f32_e32 v1, v1
	v_sub_f32_e32 v2, 1.0, v153
	v_log_f32_e32 v2, v2
	v_lshlrev_b32_e32 v152, 16, v15
	v_max_f32_e32 v17, 0xc1a00000, v0
	v_mul_f32_e32 v0, 0x3f317218, v1
	v_sub_f32_e32 v1, 1.0, v152
	v_lshlrev_b32_e32 v151, 16, v14
	v_max_f32_e32 v18, 0xc1a00000, v0
	v_mul_f32_e32 v0, 0x3f317218, v2
	v_log_f32_e32 v1, v1
	v_sub_f32_e32 v2, 1.0, v151
	v_log_f32_e32 v2, v2
	v_lshlrev_b32_e32 v150, 16, v13
	v_max_f32_e32 v19, 0xc1a00000, v0
	v_mul_f32_e32 v0, 0x3f317218, v1
	v_sub_f32_e32 v1, 1.0, v150
	v_lshlrev_b32_e32 v149, 16, v12
	v_max_f32_e32 v20, 0xc1a00000, v0
	v_mul_f32_e32 v0, 0x3f317218, v2
	v_log_f32_e32 v1, v1
	v_sub_f32_e32 v2, 1.0, v149
	v_log_f32_e32 v2, v2
	v_lshlrev_b32_e32 v148, 16, v11
	v_max_f32_e32 v21, 0xc1a00000, v0
	v_mul_f32_e32 v0, 0x3f317218, v1
	v_sub_f32_e32 v1, 1.0, v148
	v_lshlrev_b32_e32 v147, 16, v10
	v_max_f32_e32 v22, 0xc1a00000, v0
	v_mul_f32_e32 v0, 0x3f317218, v2
	v_log_f32_e32 v1, v1
	v_sub_f32_e32 v2, 1.0, v147
	v_log_f32_e32 v2, v2
	v_lshlrev_b32_e32 v146, 16, v9
	v_max_f32_e32 v23, 0xc1a00000, v0
	v_mul_f32_e32 v0, 0x3f317218, v1
	v_sub_f32_e32 v1, 1.0, v146
	v_lshlrev_b32_e32 v145, 16, v8
	v_max_f32_e32 v24, 0xc1a00000, v0
	v_mul_f32_e32 v0, 0x3f317218, v2
	v_log_f32_e32 v1, v1
	v_sub_f32_e32 v2, 1.0, v145
	v_log_f32_e32 v2, v2
	v_lshlrev_b32_e32 v87, 16, v7
	v_max_f32_e32 v25, 0xc1a00000, v0
	v_mul_f32_e32 v0, 0x3f317218, v1
	v_sub_f32_e32 v1, 1.0, v87
	v_lshlrev_b32_e32 v85, 16, v6
	v_max_f32_e32 v26, 0xc1a00000, v0
	v_mul_f32_e32 v0, 0x3f317218, v2
	v_log_f32_e32 v1, v1
	v_sub_f32_e32 v2, 1.0, v85
	v_log_f32_e32 v2, v2
	v_lshlrev_b32_e32 v83, 16, v5
	v_max_f32_e32 v27, 0xc1a00000, v0
	v_mul_f32_e32 v0, 0x3f317218, v1
	v_sub_f32_e32 v1, 1.0, v83
	v_lshlrev_b32_e32 v81, 16, v4
	v_max_f32_e32 v28, 0xc1a00000, v0
	v_mul_f32_e32 v0, 0x3f317218, v2
	v_log_f32_e32 v1, v1
	v_sub_f32_e32 v2, 1.0, v81
	v_log_f32_e32 v2, v2
	v_max_f32_e32 v29, 0xc1a00000, v0
	v_mul_f32_e32 v0, 0x3f317218, v1
	v_max_f32_e32 v30, 0xc1a00000, v0
	v_mul_f32_e32 v0, 0x3f317218, v2
	v_max_f32_e32 v31, 0xc1a00000, v0
	s_barrier
	s_and_saveexec_b64 s[12:13], s[38:39]
	s_xor_b64 vcc, exec, s[12:13]
	s_cbranch_execz .LBB0_1058
	v_add_f32_e32 v30, v30, v31
	v_add_f32_e32 v29, v29, v30
	v_add_f32_e32 v28, v28, v29
	v_add_f32_e32 v27, v27, v28
	v_add_f32_e32 v26, v26, v27
	v_add_f32_e32 v25, v25, v26
	v_add_f32_e32 v24, v24, v25
	v_add_f32_e32 v23, v23, v24
	v_add_f32_e32 v22, v22, v23
	v_add_f32_e32 v21, v21, v22
	v_add_f32_e32 v20, v20, v21
	v_add_f32_e32 v19, v19, v20
	v_add_f32_e32 v18, v18, v19
	v_add_f32_e32 v17, v17, v18
	v_add_f32_e32 v16, v16, v17
	v_mov_b64_e32 v[0:1], v[16:17]
	v_mov_b64_e32 v[2:3], v[18:19]
	v_mov_b64_e32 v[4:5], v[20:21]
	v_mov_b64_e32 v[6:7], v[22:23]
	v_mov_b64_e32 v[8:9], v[24:25]
	v_mov_b64_e32 v[10:11], v[26:27]
	v_mov_b64_e32 v[12:13], v[28:29]
	v_mov_b64_e32 v[14:15], v[30:31]

; DEV float bflo(unsigned w) { return __uint_as_float(w << 16); }
; DEV float bfhi(unsigned w) { return __uint_as_float(w & 0xffff0000u); }
; DEV void hg3_item(const Params& p, int l, int item, char* smem, int tid, const u16 (&kr)[16]) {
;     ...
;   if (dir == 0) {
;     float ss = 0.f;
; #pragma unroll
;     for (int vt = 0; vt < 4; ++vt) {
;       o[vt] += xch[(tt * 4 + vt) * 64 + lane];
;       ss += o[vt][0] * o[vt][0] + o[vt][1] * o[vt][1] + o[vt][2] * o[vt][2] + o[vt][3] * o[vt][3];
;     }
;     ss += shx(ss, 16, lane);
;     ss += shx(ss, 32, lane);
;     const float rstd = rsqrtf(ss * (1.f / 64.f) + 1e-6f);
; #pragma unroll
;     for (int vt = 0; vt < 4; ++vt) {
;       const int col = head * 64 + vt * 16 + fq * 4;
;       const float4 gn = *(const float4*)(p.hg_norm_g + l * 512 + col);
;       uint2 ov;
;       ov.x = pack2(o[vt][0] * rstd * gn.x * bflo(gz[vt].x), o[vt][1] * rstd * gn.y * bfhi(gz[vt].x));
;       ov.y = pack2(o[vt][2] * rstd * gn.z * bflo(gz[vt].y), o[vt][3] * rstd * gn.w * bfhi(gz[vt].y));
;       *(uint2*)(p.Y + ((long)TG + rfin) * 512 + col) = ov;
;     }
.LBB0_1116:
	s_or_b64 exec, exec, s[12:13]
	s_waitcnt lgkmcnt(0)
	s_barrier
	s_and_saveexec_b64 s[74:75], s[40:41]
	s_cbranch_execz .LBB0_1043
	v_or_b32_e32 v144, s79, v78
	v_lshlrev_b32_e32 v144, 2, v144
	global_load_dwordx4 v[128:131], v144, s[10:11]
	global_load_dwordx4 v[132:135], v144, s[10:11] offset:64
	global_load_dwordx4 v[136:139], v144, s[10:11] offset:128
	global_load_dwordx4 v[140:143], v144, s[10:11] offset:192
	ds_read_b128 v[0:3], v108
	s_mov_b32 s12, 0x800000
	v_readlane_b32 s20, v254, 62
	v_readlane_b32 s21, v254, 63
	v_readlane_b32 s22, v255, 0
	s_waitcnt lgkmcnt(0)
	v_pk_add_f32 v[14:15], v[22:23], v[2:3]
	v_pk_add_f32 v[20:21], v[20:21], v[0:1]
	ds_read_b128 v[0:3], v108 offset:1024
	v_readlane_b32 s23, v255, 1
	s_waitcnt lgkmcnt(0)
	v_pk_add_f32 v[12:13], v[28:29], v[0:1]
	v_pk_add_f32 v[10:11], v[30:31], v[2:3]
	v_mov_b32_e32 v2, v21
	v_mov_b32_e32 v3, v13
	v_mov_b32_e32 v0, v20
	v_mov_b32_e32 v1, v12
	v_pk_mul_f32 v[2:3], v[2:3], v[2:3]
	s_nop 0
	v_pk_fma_f32 v[0:1], v[0:1], v[0:1], v[2:3]
	v_mov_b32_e32 v2, v14
	v_mov_b32_e32 v3, v10
	v_pk_fma_f32 v[0:1], v[2:3], v[2:3], v[0:1]
	v_mov_b32_e32 v2, v15
	v_mov_b32_e32 v3, v11
	v_pk_fma_f32 v[22:23], v[2:3], v[2:3], v[0:1]
	ds_read_b128 v[0:3], v108 offset:2048
	s_waitcnt lgkmcnt(0)
	v_pk_add_f32 v[6:7], v[18:19], v[2:3]
	ds_read_b128 v[2:5], v108 offset:3072
	v_pk_add_f32 v[8:9], v[16:17], v[0:1]
	v_lshlrev_b32_e32 v18, 16, v94
	v_mov_b32_e32 v16, v9
	v_and_b32_e32 v19, 0xffff0000, v94
	s_waitcnt lgkmcnt(0)
	v_pk_add_f32 v[0:1], v[26:27], v[4:5]
	v_pk_add_f32 v[4:5], v[24:25], v[2:3]
	v_mov_b32_e32 v2, v8
	v_mov_b32_e32 v17, v5
	v_mov_b32_e32 v3, v4
	v_pk_mul_f32 v[16:17], v[16:17], v[16:17]
	v_or_b32_e32 v26, s79, v78
	v_pk_fma_f32 v[2:3], v[2:3], v[2:3], v[16:17]
	v_mov_b32_e32 v16, v6
	v_mov_b32_e32 v17, v0
	v_pk_fma_f32 v[2:3], v[16:17], v[16:17], v[2:3]
	v_mov_b32_e32 v16, v7
	v_mov_b32_e32 v17, v1
	v_pk_fma_f32 v[2:3], v[16:17], v[16:17], v[2:3]
	v_add_f32_e32 v16, v22, v23
	v_add_f32_e32 v2, v16, v2
	v_add_f32_e32 v2, v2, v3
	ds_bpermute_b32 v3, v102, v2
	v_lshlrev_b64 v[16:17], 10, v[96:97]
	s_waitcnt lgkmcnt(0)
	v_add_f32_e32 v2, v2, v3
	ds_bpermute_b32 v3, v103, v2
	s_waitcnt lgkmcnt(0)
	v_add_f32_e32 v2, v2, v3
	v_fmamk_f32 v2, v2, 0x3c800000, v196
	v_cmp_gt_f32_e32 vcc, s12, v2
	v_mul_f32_e32 v3, 0x4b800000, v2
	s_nop 0
	v_cndmask_b32_e32 v2, v2, v3, vcc
	v_rsq_f32_e32 v2, v2
	s_nop 0
	v_mul_f32_e32 v3, 0x45800000, v2
	v_cndmask_b32_e32 v2, v2, v3, vcc
	v_lshlrev_b32_e32 v3, 2, v26
	v_pk_mul_f32 v[20:21], v[20:21], v[2:3] op_sel_hi:[1,0]
	v_pk_mul_f32 v[14:15], v[14:15], v[2:3] op_sel_hi:[1,0]
	v_pk_mul_f32 v[12:13], v[12:13], v[2:3] op_sel_hi:[1,0]
	v_pk_mul_f32 v[10:11], v[10:11], v[2:3] op_sel_hi:[1,0]
	v_pk_mul_f32 v[8:9], v[8:9], v[2:3] op_sel_hi:[1,0]
	v_pk_mul_f32 v[6:7], v[6:7], v[2:3] op_sel_hi:[1,0]
	v_pk_mul_f32 v[4:5], v[4:5], v[2:3] op_sel_hi:[1,0]
	v_pk_mul_f32 v[0:1], v[0:1], v[2:3] op_sel_hi:[1,0]
	s_waitcnt vmcnt(0)
	v_pk_mul_f32 v[20:21], v[128:129], v[20:21]
	s_nop 0
	v_pk_mul_f32 v[18:19], v[20:21], v[18:19]
	v_lshlrev_b32_e32 v20, 16, v95
	v_and_b32_e32 v21, 0xffff0000, v95
	v_pk_mul_f32 v[14:15], v[130:131], v[14:15]
	v_cvt_pk_bf16_f32 v18, v18, v19
	v_pk_mul_f32 v[14:15], v[14:15], v[20:21]
	v_lshlrev_b32_e32 v22, 16, v92
	v_cvt_pk_bf16_f32 v19, v14, v15
	v_lshl_add_u64 v[14:15], s[20:21], 0, v[16:17]
	v_lshl_add_u64 v[14:15], v[14:15], 0, s[96:97]
	v_lshlrev_b32_e32 v16, 1, v26
	v_mov_b32_e32 v17, v157
	v_lshl_add_u64 v[20:21], v[14:15], 0, v[16:17]
	global_store_dwordx2 v[20:21], v[18:19], off
	v_and_b32_e32 v23, 0xffff0000, v92
	v_readlane_b32 s20, v255, 22
	v_readlane_b32 s21, v255, 23
	v_readlane_b32 s22, v255, 24
	v_readlane_b32 s23, v255, 25
	s_movk_i32 s21, 0x1000
	s_movk_i32 s20, 0x2000
	v_pk_mul_f32 v[12:13], v[132:133], v[12:13]
	v_lshlrev_b32_e32 v18, 16, v93
	v_and_b32_e32 v19, 0xffff0000, v93
	v_pk_mul_f32 v[10:11], v[134:135], v[10:11]
	v_pk_mul_f32 v[12:13], v[12:13], v[22:23]
	v_pk_mul_f32 v[10:11], v[10:11], v[18:19]
	v_cvt_pk_bf16_f32 v12, v12, v13
	v_cvt_pk_bf16_f32 v13, v10, v11
	v_or_b32_e32 v10, 32, v16
	v_mov_b32_e32 v11, v157
	v_lshl_add_u64 v[10:11], v[14:15], 0, v[10:11]
	global_store_dwordx2 v[10:11], v[12:13], off
	v_lshlrev_b32_e32 v18, 16, v90
	v_and_b32_e32 v19, 0xffff0000, v90
	v_pk_mul_f32 v[8:9], v[8:9], v[136:137]
	v_lshlrev_b32_e32 v10, 16, v91
	v_and_b32_e32 v11, 0xffff0000, v91
	v_pk_mul_f32 v[6:7], v[6:7], v[138:139]
	v_pk_mul_f32 v[8:9], v[8:9], v[18:19]
	v_pk_mul_f32 v[6:7], v[6:7], v[10:11]
	v_cvt_pk_bf16_f32 v8, v8, v9
	v_cvt_pk_bf16_f32 v9, v6, v7
	v_or_b32_e32 v6, 64, v16
	v_mov_b32_e32 v7, v157
	v_lshl_add_u64 v[6:7], v[14:15], 0, v[6:7]
	global_store_dwordx2 v[6:7], v[8:9], off
	v_lshlrev_b32_e32 v10, 16, v88
	v_and_b32_e32 v11, 0xffff0000, v88
	v_pk_mul_f32 v[4:5], v[4:5], v[140:141]
	v_lshlrev_b32_e32 v6, 16, v89
	v_and_b32_e32 v7, 0xffff0000, v89
	v_pk_mul_f32 v[0:1], v[0:1], v[142:143]
	v_pk_mul_f32 v[4:5], v[4:5], v[10:11]
	v_pk_mul_f32 v[0:1], v[0:1], v[6:7]
	v_cvt_pk_bf16_f32 v4, v4, v5
	v_cvt_pk_bf16_f32 v5, v0, v1
	v_or_b32_e32 v0, 0x60, v16
	v_mov_b32_e32 v1, v157
	v_lshl_add_u64 v[0:1], v[14:15], 0, v[0:1]
	global_store_dwordx2 v[0:1], v[4:5], off
	s_branch .LBB0_1043
